# speedup vs baseline: 1.0007x; 1.0007x over previous
; __device__ __forceinline__ float bf2f(u16 v) { return __uint_as_float(((uint32_t)v) << 16); }
; __device__ __forceinline__ u16 f2bf(float a) { return (u16)(pack2(a, 0.f) & 0xffffu); }
; __global__ void __launch_bounds__(NTHREADS, 2) fwd_megakernel(Params p_arg) {
;     ...
;             const int s = itr * 8 + (lane >> 3);
;             const size_t tok = tok0 + s;
;             uint4 raw = *(const uint4*)(ZVp + tok * 512 + g * 64 + c0);
;             float4 p0 = *(const float4*)(VSS + tok * 8), p1 = *(const float4*)(VSS + tok * 8 + 4);
;             float ssum = p0.x + p0.y + p0.z + p0.w + p1.x + p1.y + p1.z + p1.w;
;             float rs = rsqrtf(ssum * (1.f / 512.f) + EPS);
;             uint32_t wv[4] = {raw.x, raw.y, raw.z, raw.w};
; #pragma unroll
;             for (int i = 0; i < 8; ++i) {
;               u16 e = (u16)((i & 1) ? (wv[i >> 1] >> 16) : (wv[i >> 1] & 0xffffu));
;               vT[(c0 + i) * 136 + s] = f2bf(bf2f(e) * rs * gv[i]);
;             }
;           }
;         }
;         __syncthreads();
;         bf16x8 vf[4][4];
; #pragma unroll
;         for (int ct = 0; ct < 4; ++ct)
; #pragma unroll
;           for (int ks = 0; ks < 4; ++ks) vf[ct][ks] = *(const bf16x8*)(vT + (ct * 16 + fr) * 136 + ks * 32 + fq * 8);
;         const u16* wsb = wl + WOFF_S + (size_t)g * 128 * 128;
; #pragma unroll 1
;         for (int tt = 0; tt < 8; ++tt) {
;           bf16x8 wf[4];
; #pragma unroll
;           for (int ks = 0; ks < 4; ++ks) wf[ks] = *(const bf16x8*)(wsb + (tt * 16 + fr) * 128 + ks * 32 + fq * 8);
.Lmxa_nopf:
	v_add_f32_e32 v20, v20, v21
	v_add_f32_e32 v20, v20, v22
	v_add_f32_e32 v20, v20, v23
	v_add_f32_e32 v20, v20, v24
	v_add_f32_e32 v20, v20, v25
	v_add_f32_e32 v20, v20, v26
	v_add_f32_e32 v20, v20, v27
	v_fmamk_f32 v20, v20, 0x3b000000, v149
	v_cmp_gt_f32_e32 vcc, s26, v20
	v_mul_f32_e32 v21, 0x4b800000, v20
	s_nop 0
	v_cndmask_b32_e32 v20, v20, v21, vcc
	v_rsq_f32_e32 v20, v20
	s_nop 0
	v_mul_f32_e32 v21, 0x45800000, v20
	v_cndmask_b32_e32 v20, v20, v21, vcc
	v_lshlrev_b32_e32 v21, 16, v16
	v_and_b32_e32 v16, 0xffff0000, v16
	v_mul_f32_e32 v16, v20, v16
	v_mul_f32_e32 v16, v3, v16
	v_cvt_pk_bf16_f32 v16, v16, s0
	ds_write_b16 v0, v16 offset:272
	v_lshlrev_b32_e32 v16, 16, v17
	v_mul_f32_e32 v16, v20, v16
	v_mul_f32_e32 v16, v4, v16
	v_cvt_pk_bf16_f32 v16, v16, s0
	ds_write_b16 v0, v16 offset:544
	v_and_b32_e32 v16, 0xffff0000, v17
	v_mul_f32_e32 v16, v20, v16
	v_mul_f32_e32 v16, v5, v16
	v_cvt_pk_bf16_f32 v16, v16, s0
	ds_write_b16 v0, v16 offset:816
	v_lshlrev_b32_e32 v16, 16, v18
	v_mul_f32_e32 v16, v20, v16
	v_mul_f32_e32 v16, v6, v16
	v_cvt_pk_bf16_f32 v16, v16, s0
	ds_write_b16 v0, v16 offset:1088
	v_and_b32_e32 v16, 0xffff0000, v18
	v_mul_f32_e32 v16, v20, v16
	v_mul_f32_e32 v16, v7, v16
	v_cvt_pk_bf16_f32 v16, v16, s0
	ds_write_b16 v0, v16 offset:1360
	v_lshlrev_b32_e32 v16, 16, v19
	v_mul_f32_e32 v16, v20, v16
	v_mul_f32_e32 v16, v8, v16
	v_cvt_pk_bf16_f32 v16, v16, s0
	ds_write_b16 v0, v16 offset:1632
	v_and_b32_e32 v16, 0xffff0000, v19
	v_mul_f32_e32 v21, v20, v21
	v_mul_f32_e32 v16, v20, v16
	v_mul_f32_e32 v21, v2, v21
	v_mul_f32_e32 v16, v9, v16
	v_cvt_pk_bf16_f32 v21, v21, s0
	v_cvt_pk_bf16_f32 v16, v16, s0
	ds_write_b16 v0, v21
	ds_write_b16 v0, v16 offset:1904
	v_mov_b32_e32 v16, v224
	v_mov_b32_e32 v17, v225
	v_mov_b32_e32 v18, v226
	v_mov_b32_e32 v19, v227
	v_mov_b32_e32 v20, v228
	v_mov_b32_e32 v21, v229
	v_mov_b32_e32 v22, v230
	v_mov_b32_e32 v23, v231
	v_mov_b32_e32 v24, v232
	v_mov_b32_e32 v25, v233
	v_mov_b32_e32 v26, v234
	v_mov_b32_e32 v27, v235
	v_add_f32_e32 v20, v20, v21
	v_add_f32_e32 v20, v20, v22
	v_add_f32_e32 v20, v20, v23
	v_add_f32_e32 v20, v20, v24
	v_add_f32_e32 v20, v20, v25
	v_add_f32_e32 v20, v20, v26
	v_add_f32_e32 v20, v20, v27
	v_fmamk_f32 v20, v20, 0x3b000000, v149
	v_cmp_gt_f32_e32 vcc, s26, v20
	v_mul_f32_e32 v21, 0x4b800000, v20
	s_nop 0
	v_cndmask_b32_e32 v20, v20, v21, vcc
	v_rsq_f32_e32 v20, v20
	s_nop 0
	v_mul_f32_e32 v21, 0x45800000, v20
	v_cndmask_b32_e32 v20, v20, v21, vcc
	v_lshlrev_b32_e32 v21, 16, v16
	v_and_b32_e32 v16, 0xffff0000, v16
	v_mul_f32_e32 v16, v20, v16
	v_mul_f32_e32 v16, v3, v16
	v_cvt_pk_bf16_f32 v16, v16, s0
	ds_write_b16 v0, v16 offset:288
	v_lshlrev_b32_e32 v16, 16, v17
	v_mul_f32_e32 v16, v20, v16
	v_mul_f32_e32 v16, v4, v16
	v_cvt_pk_bf16_f32 v16, v16, s0
	ds_write_b16 v0, v16 offset:560
	v_and_b32_e32 v16, 0xffff0000, v17
	v_mul_f32_e32 v16, v20, v16
	v_mul_f32_e32 v16, v5, v16
	v_cvt_pk_bf16_f32 v16, v16, s0
	ds_write_b16 v0, v16 offset:832
	v_lshlrev_b32_e32 v16, 16, v18
	v_mul_f32_e32 v16, v20, v16
	v_mul_f32_e32 v16, v6, v16
	v_cvt_pk_bf16_f32 v16, v16, s0
	ds_write_b16 v0, v16 offset:1104
	v_and_b32_e32 v16, 0xffff0000, v18
	v_mul_f32_e32 v16, v20, v16
	v_mul_f32_e32 v16, v7, v16
	v_cvt_pk_bf16_f32 v16, v16, s0
	ds_write_b16 v0, v16 offset:1376
	v_lshlrev_b32_e32 v16, 16, v19
	v_mul_f32_e32 v16, v20, v16
	v_mul_f32_e32 v16, v8, v16
	v_cvt_pk_bf16_f32 v16, v16, s0
	ds_write_b16 v0, v16 offset:1648
	v_and_b32_e32 v16, 0xffff0000, v19
	v_mul_f32_e32 v21, v20, v21
	v_mul_f32_e32 v16, v20, v16
	v_mul_f32_e32 v21, v2, v21
	v_mul_f32_e32 v16, v9, v16
	v_cvt_pk_bf16_f32 v21, v21, s0
	v_cvt_pk_bf16_f32 v16, v16, s0
	ds_write_b16 v0, v21 offset:16
	ds_write_b16 v0, v16 offset:1920
	v_add_u32_e32 v0, 32, v0
	s_cmpk_eq_i32 s10, 0x1000
	s_cbranch_scc0 .Lmxa_loop
	s_waitcnt lgkmcnt(0)
	s_barrier
	ds_read_b128 v[2:5], v131
	ds_read_b128 v[6:9], v131 offset:64
	ds_read_b128 v[10:13], v131 offset:128
	ds_read_b128 v[14:17], v131 offset:192
	ds_read_b128 v[18:21], v131 offset:4352
	ds_read_b128 v[22:25], v131 offset:4416
	ds_read_b128 v[26:29], v131 offset:4480
	ds_read_b128 v[30:33], v131 offset:4544
	ds_read_b128 v[34:37], v131 offset:8704
	ds_read_b128 v[38:41], v131 offset:8768
	ds_read_b128 v[42:45], v131 offset:8832
	ds_read_b128 v[46:49], v131 offset:8896
	ds_read_b128 v[50:53], v131 offset:13056
	ds_read_b128 v[54:57], v131 offset:13120
	ds_read_b128 v[58:61], v131 offset:13184
	ds_read_b128 v[62:65], v131 offset:13248
	s_add_u32 s10, s0, s36
	s_addc_u32 s11, 0, s37
	v_lshl_add_u64 v[68:69], s[10:11], 0, v[74:75]
	v_lshlrev_b64 v[66:67], 10, v[68:69]
	v_lshlrev_b64 v[68:69], 11, v[68:69]
	v_lshl_add_u64 v[66:67], v[92:93], 0, v[66:67]
	v_lshl_add_u64 v[68:69], v[94:95], 0, v[68:69]
	s_mov_b64 s[10:11], 0
	v_mov_b64_e32 v[70:71], v[90:91]
	global_load_dwordx4 v[208:211], v[70:71], off offset:-128
	global_load_dwordx4 v[212:215], v[70:71], off offset:-64
	global_load_dwordx4 v[216:219], v[70:71], off
	global_load_dwordx4 v[220:223], v[70:71], off offset:64
	v_lshl_add_u64 v[70:71], v[70:71], 0, s[48:49]
	s_waitcnt vmcnt(0)
; __device__ __forceinline__ float bf2f(u16 v) { return __uint_as_float(((uint32_t)v) << 16); }
; __device__ __forceinline__ uint2 pack4(float a, float b, float c, float d) { return make_uint2(pack2(a, b), pack2(c, d)); }
; __global__ void __launch_bounds__(NTHREADS, 2) fwd_megakernel(Params p_arg) {
;     ...
;         for (int tt = 0; tt < 8; ++tt) {
;           bf16x8 wf[4];
; #pragma unroll
;           for (int ks = 0; ks < 4; ++ks) wf[ks] = *(const bf16x8*)(wsb + (tt * 16 + fr) * 128 + ks * 32 + fq * 8);
;           f32x4 ac[4];
; #pragma unroll
;           for (int ct = 0; ct < 4; ++ct) ac[ct] = f32x4{0.f, 0.f, 0.f, 0.f};
; #pragma unroll
;           for (int ks = 0; ks < 4; ++ks)
; #pragma unroll
;             for (int ct = 0; ct < 4; ++ct) ac[ct] = __builtin_amdgcn_mfma_f32_16x16x32_bf16(vf[ct][ks], wf[ks], ac[ct], 0, 0, 0);
;           const size_t tok = tok0 + tt * 16 + fr;
;           const float bias = pk->gm_b_s[((size_t)l * 8 + g) * 128 + tt * 16 + fr];
; #pragma unroll
;           for (int cp = 0; cp < 2; ++cp) {
;             uint2 ur[2], ov[2];
;             load_pair16(ZUp + tok * 512 + g * 64 + cp * 32, fq, ur[0], ur[1]);
; #pragma unroll
;             for (int q = 0; q < 2; ++q) {
;               const int ct = cp * 2 + q;
;               float u0 = bf2f((u16)(ur[q].x & 0xffffu)), u1 = bf2f((u16)(ur[q].x >> 16)), u2 = bf2f((u16)(ur[q].y & 0xffffu)), u3 = bf2f((u16)(ur[q].y >> 16));
;               ov[q] = pack4(u0 * (ac[ct][0] + bias), u1 * (ac[ct][1] + bias), u2 * (ac[ct][2] + bias), u3 * (ac[ct][3] + bias));
;             }
;             store_pair16(ABp + tok * 1024 + g * 64 + cp * 32, fq, ov[0], ov[1]);
;           }
.LBB0_297:
	s_waitcnt vmcnt(2)
	v_mov_b32_e32 v102, v208
	v_mov_b32_e32 v103, v209
	v_mov_b32_e32 v104, v210
	v_mov_b32_e32 v105, v211
	v_mov_b32_e32 v106, v212
	v_mov_b32_e32 v107, v213
	v_mov_b32_e32 v108, v214
	v_mov_b32_e32 v109, v215
	v_mov_b32_e32 v154, v216
	v_mov_b32_e32 v155, v217
	v_mov_b32_e32 v156, v218
	v_mov_b32_e32 v157, v219
	v_mov_b32_e32 v158, v220
	v_mov_b32_e32 v159, v221
	v_mov_b32_e32 v160, v222
	v_mov_b32_e32 v161, v223
	global_load_dwordx4 v[208:211], v[70:71], off offset:-128
	global_load_dwordx4 v[212:215], v[70:71], off offset:-64
	global_load_dwordx4 v[216:219], v[70:71], off
	global_load_dwordx4 v[220:223], v[70:71], off offset:64
	v_lshl_add_u64 v[72:73], v[88:89], 0, s[10:11]
	global_load_dword v0, v[72:73], off
	v_lshl_add_u64 v[72:73], v[66:67], 0, s[34:35]
	global_load_dwordx4 v[192:195], v[72:73], off
	global_load_dwordx4 v[196:199], v[72:73], off offset:64
	v_lshl_add_u64 v[110:111], v[68:69], 0, s[34:35]
	s_add_u32 s10, s10, 64
	s_addc_u32 s11, s11, 0
	s_mov_b64 s[12:13], 0x8000
	v_lshl_add_u64 v[70:71], v[70:71], 0, s[48:49]
	v_lshl_add_u64 v[66:67], v[66:67], 0, s[94:95]
	v_lshl_add_u64 v[68:69], v[68:69], 0, s[12:13]
	s_cmpk_eq_i32 s10, 0x200
	s_waitcnt lgkmcnt(14)
	v_mfma_f32_16x16x32_bf16 v[180:183], v[2:5], v[102:105], 0
	s_waitcnt lgkmcnt(11)
	v_mfma_f32_16x16x32_bf16 v[184:187], v[18:21], v[102:105], 0
	s_waitcnt lgkmcnt(7)
	v_mfma_f32_16x16x32_bf16 v[188:191], v[34:37], v[102:105], 0
	s_waitcnt lgkmcnt(3)
	v_mfma_f32_16x16x32_bf16 v[102:105], v[50:53], v[102:105], 0
	v_mfma_f32_16x16x32_bf16 v[180:183], v[6:9], v[106:109], v[180:183]
	v_mfma_f32_16x16x32_bf16 v[184:187], v[22:25], v[106:109], v[184:187]
	v_mfma_f32_16x16x32_bf16 v[188:191], v[38:41], v[106:109], v[188:191]
	s_waitcnt lgkmcnt(2)
	v_mfma_f32_16x16x32_bf16 v[102:105], v[54:57], v[106:109], v[102:105]
	v_mfma_f32_16x16x32_bf16 v[106:109], v[10:13], v[154:157], v[180:183]
	v_mfma_f32_16x16x32_bf16 v[180:183], v[26:29], v[154:157], v[184:187]
	v_mfma_f32_16x16x32_bf16 v[184:187], v[42:45], v[154:157], v[188:191]
	s_waitcnt lgkmcnt(1)
	v_mfma_f32_16x16x32_bf16 v[102:105], v[58:61], v[154:157], v[102:105]
	v_mfma_f32_16x16x32_bf16 v[106:109], v[14:17], v[158:161], v[106:109]
	v_mfma_f32_16x16x32_bf16 v[154:157], v[30:33], v[158:161], v[180:183]
	v_mfma_f32_16x16x32_bf16 v[180:183], v[46:49], v[158:161], v[184:187]
	s_waitcnt vmcnt(2)
	s_nop 4
	v_pk_add_f32 v[106:107], v[0:1], v[106:107] op_sel_hi:[0,1]
	v_pk_add_f32 v[108:109], v[0:1], v[108:109] op_sel_hi:[0,1]
	v_pk_add_f32 v[154:155], v[0:1], v[154:155] op_sel_hi:[0,1]
	s_waitcnt lgkmcnt(0)
	v_mfma_f32_16x16x32_bf16 v[102:105], v[62:65], v[158:161], v[102:105]
	s_waitcnt vmcnt(1)
	v_mov_b32_e32 v101, v194
	v_mov_b32_e32 v151, v195
	s_nop 0
	v_permlane16_swap_b32_e32 v192, v101
	v_permlane16_swap_b32_e32 v193, v151
	v_lshlrev_b32_e32 v160, 16, v192
	v_and_b32_e32 v161, 0xffff0000, v192
	v_lshlrev_b32_e32 v158, 16, v193
	v_and_b32_e32 v159, 0xffff0000, v193
	v_pk_mul_f32 v[106:107], v[106:107], v[160:161]
	v_pk_mul_f32 v[108:109], v[108:109], v[158:159]
	v_cvt_pk_bf16_f32 v106, v106, v107
	v_cvt_pk_bf16_f32 v107, v108, v109
	v_lshlrev_b32_e32 v108, 16, v101
	v_and_b32_e32 v109, 0xffff0000, v101
	v_lshlrev_b32_e32 v158, 16, v151
	v_and_b32_e32 v159, 0xffff0000, v151
	v_pk_mul_f32 v[108:109], v[154:155], v[108:109]
	v_pk_add_f32 v[154:155], v[0:1], v[156:157] op_sel_hi:[0,1]
	v_pk_mul_f32 v[154:155], v[154:155], v[158:159]
	v_cvt_pk_bf16_f32 v108, v108, v109
	v_cvt_pk_bf16_f32 v109, v154, v155
	s_nop 0
	v_permlane16_swap_b32_e32 v106, v108
	v_permlane16_swap_b32_e32 v107, v109
	global_store_dwordx4 v[110:111], v[106:109], off offset:-64
	v_pk_add_f32 v[102:103], v[0:1], v[102:103] op_sel_hi:[0,1]
	s_waitcnt vmcnt(1)
	v_mov_b32_e32 v101, v198
	s_nop 1
	v_permlane16_swap_b32_e32 v196, v101
	v_mov_b32_e32 v151, v199
	s_nop 1
	v_permlane16_swap_b32_e32 v197, v151
	v_lshlrev_b32_e32 v72, 16, v196
	v_and_b32_e32 v73, 0xffff0000, v196
	v_pk_add_f32 v[108:109], v[0:1], v[180:181] op_sel_hi:[0,1]
	v_lshlrev_b32_e32 v106, 16, v197
	v_and_b32_e32 v107, 0xffff0000, v197
	v_pk_mul_f32 v[72:73], v[108:109], v[72:73]
	v_pk_add_f32 v[108:109], v[0:1], v[182:183] op_sel_hi:[0,1]
	v_pk_mul_f32 v[108:109], v[108:109], v[106:107]
	v_cvt_pk_bf16_f32 v106, v72, v73
	v_lshlrev_b32_e32 v72, 16, v101
	v_and_b32_e32 v73, 0xffff0000, v101
	v_cvt_pk_bf16_f32 v107, v108, v109
	v_lshlrev_b32_e32 v108, 16, v151
	v_and_b32_e32 v109, 0xffff0000, v151
	v_pk_mul_f32 v[72:73], v[102:103], v[72:73]
	v_pk_add_f32 v[102:103], v[0:1], v[104:105] op_sel_hi:[0,1]
	v_pk_mul_f32 v[102:103], v[102:103], v[108:109]
	v_cvt_pk_bf16_f32 v108, v72, v73
	v_cvt_pk_bf16_f32 v109, v102, v103
	s_nop 0
	v_permlane16_swap_b32_e32 v106, v108
	v_permlane16_swap_b32_e32 v107, v109
	global_store_dwordx4 v[110:111], v[106:109], off
	s_cbranch_scc0 .LBB0_297
; __global__ void __launch_bounds__(NTHREADS, 2) fwd_megakernel(Params p_arg) {
;     ...
;         const int qt = wid;
;         const int kt0 = qt < 6 ? qt : 6;
;         const int qi = qt * 16 + fr;
;         const float klo = (nb == 0) ? 128.f : 0.f, khi = (nb == 31) ? 256.f : 384.f;
; #pragma unroll 1
;         for (int g = 0; g < 4; ++g) {
;           const int h = kvh * 4 + g;
;           const size_t tokq = tok0 + qt * 16 + fr;
;           bf16x8 qf[2];
;           qf[0] = *(const bf16x8*)(ZQp + tokq * 512 + h * 64 + fq * 8);
;           qf[1] = *(const bf16x8*)(ZQp + tokq * 512 + h * 64 + 32 + fq * 8);
;           f32x4 S[18];
; #pragma unroll
;           for (int i = 0; i < 18; ++i) {
;             S[i] = f32x4{0.f, 0.f, 0.f, 0.f};
; #pragma unroll
;             for (int ks = 0; ks < 2; ++ks) {
;               bf16x8 kf = *(const bf16x8*)(Ks + ((kt0 + i) * 16 + fr) * 72 + ks * 32 + fq * 8);
;               S[i] = __builtin_amdgcn_mfma_f32_16x16x32_bf16(kf, qf[ks], S[i], 0, 0, 0);
;             }
;             if ((i % 3) == 2) __builtin_amdgcn_sched_barrier(0);
;           }
;           const float slope = exp2f(-(float)(h + 1));
;           const float sinkv = pk->attn_sink[(size_t)l * 8 + h];
;           float d0 = (float)(kt0 * 16 + fq * 4 - 128 - qi);
;           asm volatile("" : "+v"(d0));
;           const float lo2 = fmaxf(-128.f, klo - 128.f - (float)qi), hi2 = fminf(128.f, khi - 129.f - (float)qi);
;           float mx = sinkv;
; #pragma unroll
;           for (int i = 0; i < 18; ++i)
; #pragma unroll
;             for (int r = 0; r < 4; ++r) {
;               float t = d0 + (float)(i * 16 + r);
;               bool ok = (t >= lo2) && (t <= hi2);
;               float v = ok ? (S[i][r] - slope * fabsf(t)) : -1e30f;
;               S[i][r] = v; mx = fmaxf(mx, v);
;             }
	s_and_b32 s1, s99, 31
	s_lshl_b32 s47, s1, 7
	s_cmp_eq_u32 s1, 0
	s_cselect_b64 s[10:11], -1, 0
	s_cmp_eq_u32 s1, 31
	v_cndmask_b32_e64 v0, v165, 0, s[10:11]
	v_sub_f32_e32 v0, v0, v113
	s_cselect_b64 vcc, -1, 0
	v_max_f32_e32 v153, 0xc3000000, v0
	v_cndmask_b32_e32 v0, v254, v168, vcc
	s_addk_i32 s47, 0xff80
	v_sub_f32_e32 v0, v0, v113
	s_add_u32 s0, s0, s36
	v_min_f32_e32 v154, 0x43000000, v0
	v_add_u32_e32 v0, s47, v127
	s_addc_u32 s1, 0, s37
	v_or_b32_e32 v2, s36, v0
	v_mov_b32_e32 v3, s37
	v_lshl_add_u64 v[4:5], s[0:1], 0, v[78:79]
	v_lshlrev_b64 v[2:3], 7, v[2:3]
	v_lshlrev_b64 v[6:7], 10, v[4:5]
	v_lshlrev_b64 v[4:5], 11, v[4:5]
	s_mov_b32 s28, 0
	v_cmp_gt_u32_e64 s[10:11], s38, v0
	v_lshl_add_u64 v[102:103], v[96:97], 0, v[6:7]
	v_lshl_add_u64 v[104:105], v[98:99], 0, v[4:5]
	s_mov_b64 s[12:13], -1
	v_lshlrev_b64 v[106:107], 1, v[2:3]
	v_mov_b32_e32 v249, 0x7f7f0000
	v_add_f32_e32 v247, 0x00000000, v112
	v_cmp_ge_f32_e32 vcc, v247, v153
	v_cmp_le_f32_e64 s[14:15], v247, v154
	v_and_b32_e32 v247, 0x7fffffff, v247
	s_and_b64 vcc, vcc, s[14:15]
	s_nop 1
	v_cndmask_b32_e32 v245, v249, v247, vcc
	v_add_f32_e32 v248, 0x3f800000, v112
	v_cmp_ge_f32_e32 vcc, v248, v153
	v_cmp_le_f32_e64 s[14:15], v248, v154
	v_and_b32_e32 v248, 0x7fffffff, v248
	s_and_b64 vcc, vcc, s[14:15]
	s_nop 1
	v_cndmask_b32_e32 v246, v249, v248, vcc
	v_cvt_pk_bf16_f32 v208, v245, v246
	v_add_f32_e32 v247, 0x40000000, v112
	v_cmp_ge_f32_e32 vcc, v247, v153
	v_cmp_le_f32_e64 s[14:15], v247, v154
	v_and_b32_e32 v247, 0x7fffffff, v247
	s_and_b64 vcc, vcc, s[14:15]
	s_nop 1
	v_cndmask_b32_e32 v245, v249, v247, vcc
	v_add_f32_e32 v248, 0x40400000, v112
	v_cmp_ge_f32_e32 vcc, v248, v153
	v_cmp_le_f32_e64 s[14:15], v248, v154
	v_and_b32_e32 v248, 0x7fffffff, v248
	s_and_b64 vcc, vcc, s[14:15]
	s_nop 1
	v_cndmask_b32_e32 v246, v249, v248, vcc
	v_cvt_pk_bf16_f32 v209, v245, v246
	v_add_f32_e32 v247, 0x41800000, v112
	v_cmp_ge_f32_e32 vcc, v247, v153
	v_cmp_le_f32_e64 s[14:15], v247, v154
	v_and_b32_e32 v247, 0x7fffffff, v247
	s_and_b64 vcc, vcc, s[14:15]
	s_nop 1
	v_cndmask_b32_e32 v245, v249, v247, vcc
	v_add_f32_e32 v248, 0x41880000, v112
	v_cmp_ge_f32_e32 vcc, v248, v153
	v_cmp_le_f32_e64 s[14:15], v248, v154
	v_and_b32_e32 v248, 0x7fffffff, v248
	s_and_b64 vcc, vcc, s[14:15]
	s_nop 1
	v_cndmask_b32_e32 v246, v249, v248, vcc
	v_cvt_pk_bf16_f32 v210, v245, v246
	v_add_f32_e32 v247, 0x41900000, v112
	v_cmp_ge_f32_e32 vcc, v247, v153
	v_cmp_le_f32_e64 s[14:15], v247, v154
	v_and_b32_e32 v247, 0x7fffffff, v247
	s_and_b64 vcc, vcc, s[14:15]
	s_nop 1
	v_cndmask_b32_e32 v245, v249, v247, vcc
	v_add_f32_e32 v248, 0x41980000, v112
	v_cmp_ge_f32_e32 vcc, v248, v153
	v_cmp_le_f32_e64 s[14:15], v248, v154
	v_and_b32_e32 v248, 0x7fffffff, v248
	s_and_b64 vcc, vcc, s[14:15]
	s_nop 1
	v_cndmask_b32_e32 v246, v249, v248, vcc
	v_cvt_pk_bf16_f32 v211, v245, v246
	v_add_f32_e32 v247, 0x42000000, v112
	v_cmp_ge_f32_e32 vcc, v247, v153
	v_cmp_le_f32_e64 s[14:15], v247, v154
	v_and_b32_e32 v247, 0x7fffffff, v247
	s_and_b64 vcc, vcc, s[14:15]
	s_nop 1
	v_cndmask_b32_e32 v245, v249, v247, vcc
	v_add_f32_e32 v248, 0x42040000, v112
	v_cmp_ge_f32_e32 vcc, v248, v153
	v_cmp_le_f32_e64 s[14:15], v248, v154
	v_and_b32_e32 v248, 0x7fffffff, v248
	s_and_b64 vcc, vcc, s[14:15]
	s_nop 1
	v_cndmask_b32_e32 v246, v249, v248, vcc
	v_cvt_pk_bf16_f32 v212, v245, v246
	v_add_f32_e32 v247, 0x42080000, v112
	v_cmp_ge_f32_e32 vcc, v247, v153
	v_cmp_le_f32_e64 s[14:15], v247, v154
	v_and_b32_e32 v247, 0x7fffffff, v247
	s_and_b64 vcc, vcc, s[14:15]
	s_nop 1
	v_cndmask_b32_e32 v245, v249, v247, vcc
	v_add_f32_e32 v248, 0x420c0000, v112
	v_cmp_ge_f32_e32 vcc, v248, v153
	v_cmp_le_f32_e64 s[14:15], v248, v154
	v_and_b32_e32 v248, 0x7fffffff, v248
	s_and_b64 vcc, vcc, s[14:15]
	s_nop 1
	v_cndmask_b32_e32 v246, v249, v248, vcc
	v_cvt_pk_bf16_f32 v213, v245, v246
	v_add_f32_e32 v247, 0x42400000, v112
	v_cmp_ge_f32_e32 vcc, v247, v153
	v_cmp_le_f32_e64 s[14:15], v247, v154
	v_and_b32_e32 v247, 0x7fffffff, v247
	s_and_b64 vcc, vcc, s[14:15]
	s_nop 1
	v_cndmask_b32_e32 v245, v249, v247, vcc
	v_add_f32_e32 v248, 0x42440000, v112
	v_cmp_ge_f32_e32 vcc, v248, v153
	v_cmp_le_f32_e64 s[14:15], v248, v154
	v_and_b32_e32 v248, 0x7fffffff, v248
	s_and_b64 vcc, vcc, s[14:15]
	s_nop 1
	v_cndmask_b32_e32 v246, v249, v248, vcc
	v_cvt_pk_bf16_f32 v214, v245, v246
	v_add_f32_e32 v247, 0x42480000, v112
	v_cmp_ge_f32_e32 vcc, v247, v153
	v_cmp_le_f32_e64 s[14:15], v247, v154
	v_and_b32_e32 v247, 0x7fffffff, v247
	s_and_b64 vcc, vcc, s[14:15]
	s_nop 1
	v_cndmask_b32_e32 v245, v249, v247, vcc
	v_add_f32_e32 v248, 0x424c0000, v112
	v_cmp_ge_f32_e32 vcc, v248, v153
	v_cmp_le_f32_e64 s[14:15], v248, v154
	v_and_b32_e32 v248, 0x7fffffff, v248
	s_and_b64 vcc, vcc, s[14:15]
	s_nop 1
	v_cndmask_b32_e32 v246, v249, v248, vcc
	v_cvt_pk_bf16_f32 v215, v245, v246
	v_add_f32_e32 v247, 0x42800000, v112
	v_cmp_ge_f32_e32 vcc, v247, v153
	v_cmp_le_f32_e64 s[14:15], v247, v154
	v_and_b32_e32 v247, 0x7fffffff, v247
	s_and_b64 vcc, vcc, s[14:15]
	s_nop 1
	v_cndmask_b32_e32 v245, v249, v247, vcc
	v_add_f32_e32 v248, 0x42820000, v112
	v_cmp_ge_f32_e32 vcc, v248, v153
	v_cmp_le_f32_e64 s[14:15], v248, v154
	v_and_b32_e32 v248, 0x7fffffff, v248
	s_and_b64 vcc, vcc, s[14:15]
	s_nop 1
	v_cndmask_b32_e32 v246, v249, v248, vcc
	v_cvt_pk_bf16_f32 v216, v245, v246
	v_add_f32_e32 v247, 0x42840000, v112
	v_cmp_ge_f32_e32 vcc, v247, v153
	v_cmp_le_f32_e64 s[14:15], v247, v154
	v_and_b32_e32 v247, 0x7fffffff, v247
	s_and_b64 vcc, vcc, s[14:15]
	s_nop 1
	v_cndmask_b32_e32 v245, v249, v247, vcc
	v_add_f32_e32 v248, 0x42860000, v112
	v_cmp_ge_f32_e32 vcc, v248, v153
; __global__ void __launch_bounds__(NTHREADS, 2) fwd_megakernel(Params p_arg) {
;     ...
;           float d0 = (float)(kt0 * 16 + fq * 4 - 128 - qi);
;           asm volatile("" : "+v"(d0));
;           const float lo2 = fmaxf(-128.f, klo - 128.f - (float)qi), hi2 = fminf(128.f, khi - 129.f - (float)qi);
;           float mx = sinkv;
; #pragma unroll
;           for (int i = 0; i < 18; ++i)
; #pragma unroll
;             for (int r = 0; r < 4; ++r) {
;               float t = d0 + (float)(i * 16 + r);
;               bool ok = (t >= lo2) && (t <= hi2);
;               float v = ok ? (S[i][r] - slope * fabsf(t)) : -1e30f;
;               S[i][r] = v; mx = fmaxf(mx, v);
	v_cmp_le_f32_e64 s[14:15], v248, v154
	v_and_b32_e32 v248, 0x7fffffff, v248
	s_and_b64 vcc, vcc, s[14:15]
	s_nop 1
	v_cndmask_b32_e32 v246, v249, v248, vcc
	v_cvt_pk_bf16_f32 v217, v245, v246
	v_add_f32_e32 v247, 0x42a00000, v112
	v_cmp_ge_f32_e32 vcc, v247, v153
	v_cmp_le_f32_e64 s[14:15], v247, v154
	v_and_b32_e32 v247, 0x7fffffff, v247
	s_and_b64 vcc, vcc, s[14:15]
	s_nop 1
	v_cndmask_b32_e32 v245, v249, v247, vcc
	v_add_f32_e32 v248, 0x42a20000, v112
	v_cmp_ge_f32_e32 vcc, v248, v153
	v_cmp_le_f32_e64 s[14:15], v248, v154
	v_and_b32_e32 v248, 0x7fffffff, v248
	s_and_b64 vcc, vcc, s[14:15]
	s_nop 1
	v_cndmask_b32_e32 v246, v249, v248, vcc
	v_cvt_pk_bf16_f32 v218, v245, v246
	v_add_f32_e32 v247, 0x42a40000, v112
	v_cmp_ge_f32_e32 vcc, v247, v153
	v_cmp_le_f32_e64 s[14:15], v247, v154
	v_and_b32_e32 v247, 0x7fffffff, v247
	s_and_b64 vcc, vcc, s[14:15]
	s_nop 1
	v_cndmask_b32_e32 v245, v249, v247, vcc
	v_add_f32_e32 v248, 0x42a60000, v112
	v_cmp_ge_f32_e32 vcc, v248, v153
	v_cmp_le_f32_e64 s[14:15], v248, v154
	v_and_b32_e32 v248, 0x7fffffff, v248
	s_and_b64 vcc, vcc, s[14:15]
	s_nop 1
	v_cndmask_b32_e32 v246, v249, v248, vcc
	v_cvt_pk_bf16_f32 v219, v245, v246
	v_add_f32_e32 v247, 0x42c00000, v112
	v_cmp_ge_f32_e32 vcc, v247, v153
	v_cmp_le_f32_e64 s[14:15], v247, v154
	v_and_b32_e32 v247, 0x7fffffff, v247
	s_and_b64 vcc, vcc, s[14:15]
	s_nop 1
	v_cndmask_b32_e32 v245, v249, v247, vcc
	v_add_f32_e32 v248, 0x42c20000, v112
	v_cmp_ge_f32_e32 vcc, v248, v153
	v_cmp_le_f32_e64 s[14:15], v248, v154
	v_and_b32_e32 v248, 0x7fffffff, v248
	s_and_b64 vcc, vcc, s[14:15]
	s_nop 1
	v_cndmask_b32_e32 v246, v249, v248, vcc
	v_cvt_pk_bf16_f32 v220, v245, v246
	v_add_f32_e32 v247, 0x42c40000, v112
	v_cmp_ge_f32_e32 vcc, v247, v153
	v_cmp_le_f32_e64 s[14:15], v247, v154
	v_and_b32_e32 v247, 0x7fffffff, v247
	s_and_b64 vcc, vcc, s[14:15]
	s_nop 1
	v_cndmask_b32_e32 v245, v249, v247, vcc
	v_add_f32_e32 v248, 0x42c60000, v112
	v_cmp_ge_f32_e32 vcc, v248, v153
	v_cmp_le_f32_e64 s[14:15], v248, v154
	v_and_b32_e32 v248, 0x7fffffff, v248
	s_and_b64 vcc, vcc, s[14:15]
	s_nop 1
	v_cndmask_b32_e32 v246, v249, v248, vcc
	v_cvt_pk_bf16_f32 v221, v245, v246
	v_add_f32_e32 v247, 0x42e00000, v112
	v_cmp_ge_f32_e32 vcc, v247, v153
	v_cmp_le_f32_e64 s[14:15], v247, v154
	v_and_b32_e32 v247, 0x7fffffff, v247
	s_and_b64 vcc, vcc, s[14:15]
	s_nop 1
	v_cndmask_b32_e32 v245, v249, v247, vcc
	v_add_f32_e32 v248, 0x42e20000, v112
	v_cmp_ge_f32_e32 vcc, v248, v153
	v_cmp_le_f32_e64 s[14:15], v248, v154
	v_and_b32_e32 v248, 0x7fffffff, v248
	s_and_b64 vcc, vcc, s[14:15]
	s_nop 1
	v_cndmask_b32_e32 v246, v249, v248, vcc
	v_cvt_pk_bf16_f32 v222, v245, v246
	v_add_f32_e32 v247, 0x42e40000, v112
	v_cmp_ge_f32_e32 vcc, v247, v153
	v_cmp_le_f32_e64 s[14:15], v247, v154
	v_and_b32_e32 v247, 0x7fffffff, v247
	s_and_b64 vcc, vcc, s[14:15]
	s_nop 1
	v_cndmask_b32_e32 v245, v249, v247, vcc
	v_add_f32_e32 v248, 0x42e60000, v112
	v_cmp_ge_f32_e32 vcc, v248, v153
	v_cmp_le_f32_e64 s[14:15], v248, v154
	v_and_b32_e32 v248, 0x7fffffff, v248
	s_and_b64 vcc, vcc, s[14:15]
	s_nop 1
	v_cndmask_b32_e32 v246, v249, v248, vcc
	v_cvt_pk_bf16_f32 v223, v245, v246
	v_add_f32_e32 v247, 0x43000000, v112
	v_cmp_ge_f32_e32 vcc, v247, v153
	v_cmp_le_f32_e64 s[14:15], v247, v154
	v_and_b32_e32 v247, 0x7fffffff, v247
	s_and_b64 vcc, vcc, s[14:15]
	s_nop 1
	v_cndmask_b32_e32 v245, v249, v247, vcc
	v_add_f32_e32 v248, 0x43010000, v112
	v_cmp_ge_f32_e32 vcc, v248, v153
	v_cmp_le_f32_e64 s[14:15], v248, v154
	v_and_b32_e32 v248, 0x7fffffff, v248
	s_and_b64 vcc, vcc, s[14:15]
	s_nop 1
	v_cndmask_b32_e32 v246, v249, v248, vcc
	v_cvt_pk_bf16_f32 v224, v245, v246
	v_add_f32_e32 v247, 0x43020000, v112
	v_cmp_ge_f32_e32 vcc, v247, v153
	v_cmp_le_f32_e64 s[14:15], v247, v154
	v_and_b32_e32 v247, 0x7fffffff, v247
	s_and_b64 vcc, vcc, s[14:15]
	s_nop 1
	v_cndmask_b32_e32 v245, v249, v247, vcc
	v_add_f32_e32 v248, 0x43030000, v112
	v_cmp_ge_f32_e32 vcc, v248, v153
	v_cmp_le_f32_e64 s[14:15], v248, v154
	v_and_b32_e32 v248, 0x7fffffff, v248
	s_and_b64 vcc, vcc, s[14:15]
	s_nop 1
	v_cndmask_b32_e32 v246, v249, v248, vcc
	v_cvt_pk_bf16_f32 v225, v245, v246
	v_add_f32_e32 v247, 0x43100000, v112
	v_cmp_ge_f32_e32 vcc, v247, v153
	v_cmp_le_f32_e64 s[14:15], v247, v154
	v_and_b32_e32 v247, 0x7fffffff, v247
	s_and_b64 vcc, vcc, s[14:15]
	s_nop 1
	v_cndmask_b32_e32 v245, v249, v247, vcc
	v_add_f32_e32 v248, 0x43110000, v112
	v_cmp_ge_f32_e32 vcc, v248, v153
	v_cmp_le_f32_e64 s[14:15], v248, v154
	v_and_b32_e32 v248, 0x7fffffff, v248
	s_and_b64 vcc, vcc, s[14:15]
	s_nop 1
	v_cndmask_b32_e32 v246, v249, v248, vcc
	v_cvt_pk_bf16_f32 v226, v245, v246
	v_add_f32_e32 v247, 0x43120000, v112
	v_cmp_ge_f32_e32 vcc, v247, v153
	v_cmp_le_f32_e64 s[14:15], v247, v154
	v_and_b32_e32 v247, 0x7fffffff, v247
	s_and_b64 vcc, vcc, s[14:15]
	s_nop 1
	v_cndmask_b32_e32 v245, v249, v247, vcc
	v_add_f32_e32 v248, 0x43130000, v112
	v_cmp_ge_f32_e32 vcc, v248, v153
	v_cmp_le_f32_e64 s[14:15], v248, v154
	v_and_b32_e32 v248, 0x7fffffff, v248
	s_and_b64 vcc, vcc, s[14:15]
	s_nop 1
	v_cndmask_b32_e32 v246, v249, v248, vcc
	v_cvt_pk_bf16_f32 v227, v245, v246
	v_add_f32_e32 v247, 0x43200000, v112
	v_cmp_ge_f32_e32 vcc, v247, v153
	v_cmp_le_f32_e64 s[14:15], v247, v154
	v_and_b32_e32 v247, 0x7fffffff, v247
	s_and_b64 vcc, vcc, s[14:15]
	s_nop 1
	v_cndmask_b32_e32 v245, v249, v247, vcc
	v_add_f32_e32 v248, 0x43210000, v112
	v_cmp_ge_f32_e32 vcc, v248, v153
	v_cmp_le_f32_e64 s[14:15], v248, v154
	v_and_b32_e32 v248, 0x7fffffff, v248
	s_and_b64 vcc, vcc, s[14:15]
	s_nop 1
	v_cndmask_b32_e32 v246, v249, v248, vcc
	v_cvt_pk_bf16_f32 v228, v245, v246
; __global__ void __launch_bounds__(NTHREADS, 2) fwd_megakernel(Params p_arg) {
;     ...
;           float d0 = (float)(kt0 * 16 + fq * 4 - 128 - qi);
;           asm volatile("" : "+v"(d0));
;           const float lo2 = fmaxf(-128.f, klo - 128.f - (float)qi), hi2 = fminf(128.f, khi - 129.f - (float)qi);
;           float mx = sinkv;
; #pragma unroll
;           for (int i = 0; i < 18; ++i)
; #pragma unroll
;             for (int r = 0; r < 4; ++r) {
;               float t = d0 + (float)(i * 16 + r);
;               bool ok = (t >= lo2) && (t <= hi2);
;               float v = ok ? (S[i][r] - slope * fabsf(t)) : -1e30f;
;               S[i][r] = v; mx = fmaxf(mx, v);
	v_add_f32_e32 v247, 0x43220000, v112
	v_cmp_ge_f32_e32 vcc, v247, v153
	v_cmp_le_f32_e64 s[14:15], v247, v154
	v_and_b32_e32 v247, 0x7fffffff, v247
	s_and_b64 vcc, vcc, s[14:15]
	s_nop 1
	v_cndmask_b32_e32 v245, v249, v247, vcc
	v_add_f32_e32 v248, 0x43230000, v112
	v_cmp_ge_f32_e32 vcc, v248, v153
	v_cmp_le_f32_e64 s[14:15], v248, v154
	v_and_b32_e32 v248, 0x7fffffff, v248
	s_and_b64 vcc, vcc, s[14:15]
	s_nop 1
	v_cndmask_b32_e32 v246, v249, v248, vcc
	v_cvt_pk_bf16_f32 v229, v245, v246
	v_add_f32_e32 v247, 0x43300000, v112
	v_cmp_ge_f32_e32 vcc, v247, v153
	v_cmp_le_f32_e64 s[14:15], v247, v154
	v_and_b32_e32 v247, 0x7fffffff, v247
	s_and_b64 vcc, vcc, s[14:15]
	s_nop 1
	v_cndmask_b32_e32 v245, v249, v247, vcc
	v_add_f32_e32 v248, 0x43310000, v112
	v_cmp_ge_f32_e32 vcc, v248, v153
	v_cmp_le_f32_e64 s[14:15], v248, v154
	v_and_b32_e32 v248, 0x7fffffff, v248
	s_and_b64 vcc, vcc, s[14:15]
	s_nop 1
	v_cndmask_b32_e32 v246, v249, v248, vcc
	v_cvt_pk_bf16_f32 v230, v245, v246
	v_add_f32_e32 v247, 0x43320000, v112
	v_cmp_ge_f32_e32 vcc, v247, v153
	v_cmp_le_f32_e64 s[14:15], v247, v154
	v_and_b32_e32 v247, 0x7fffffff, v247
	s_and_b64 vcc, vcc, s[14:15]
	s_nop 1
	v_cndmask_b32_e32 v245, v249, v247, vcc
	v_add_f32_e32 v248, 0x43330000, v112
	v_cmp_ge_f32_e32 vcc, v248, v153
	v_cmp_le_f32_e64 s[14:15], v248, v154
	v_and_b32_e32 v248, 0x7fffffff, v248
	s_and_b64 vcc, vcc, s[14:15]
	s_nop 1
	v_cndmask_b32_e32 v246, v249, v248, vcc
	v_cvt_pk_bf16_f32 v231, v245, v246
	v_add_f32_e32 v247, 0x43400000, v112
	v_cmp_ge_f32_e32 vcc, v247, v153
	v_cmp_le_f32_e64 s[14:15], v247, v154
	v_and_b32_e32 v247, 0x7fffffff, v247
	s_and_b64 vcc, vcc, s[14:15]
	s_nop 1
	v_cndmask_b32_e32 v245, v249, v247, vcc
	v_add_f32_e32 v248, 0x43410000, v112
	v_cmp_ge_f32_e32 vcc, v248, v153
	v_cmp_le_f32_e64 s[14:15], v248, v154
	v_and_b32_e32 v248, 0x7fffffff, v248
	s_and_b64 vcc, vcc, s[14:15]
	s_nop 1
	v_cndmask_b32_e32 v246, v249, v248, vcc
	v_cvt_pk_bf16_f32 v232, v245, v246
	v_add_f32_e32 v247, 0x43420000, v112
	v_cmp_ge_f32_e32 vcc, v247, v153
	v_cmp_le_f32_e64 s[14:15], v247, v154
	v_and_b32_e32 v247, 0x7fffffff, v247
	s_and_b64 vcc, vcc, s[14:15]
	s_nop 1
	v_cndmask_b32_e32 v245, v249, v247, vcc
	v_add_f32_e32 v248, 0x43430000, v112
	v_cmp_ge_f32_e32 vcc, v248, v153
	v_cmp_le_f32_e64 s[14:15], v248, v154
	v_and_b32_e32 v248, 0x7fffffff, v248
	s_and_b64 vcc, vcc, s[14:15]
	s_nop 1
	v_cndmask_b32_e32 v246, v249, v248, vcc
	v_cvt_pk_bf16_f32 v233, v245, v246
	v_add_f32_e32 v247, 0x43500000, v112
	v_cmp_ge_f32_e32 vcc, v247, v153
	v_cmp_le_f32_e64 s[14:15], v247, v154
	v_and_b32_e32 v247, 0x7fffffff, v247
	s_and_b64 vcc, vcc, s[14:15]
	s_nop 1
	v_cndmask_b32_e32 v245, v249, v247, vcc
	v_add_f32_e32 v248, 0x43510000, v112
	v_cmp_ge_f32_e32 vcc, v248, v153
	v_cmp_le_f32_e64 s[14:15], v248, v154
	v_and_b32_e32 v248, 0x7fffffff, v248
	s_and_b64 vcc, vcc, s[14:15]
	s_nop 1
	v_cndmask_b32_e32 v246, v249, v248, vcc
	v_cvt_pk_bf16_f32 v234, v245, v246
	v_add_f32_e32 v247, 0x43520000, v112
	v_cmp_ge_f32_e32 vcc, v247, v153
	v_cmp_le_f32_e64 s[14:15], v247, v154
	v_and_b32_e32 v247, 0x7fffffff, v247
	s_and_b64 vcc, vcc, s[14:15]
	s_nop 1
	v_cndmask_b32_e32 v245, v249, v247, vcc
	v_add_f32_e32 v248, 0x43530000, v112
	v_cmp_ge_f32_e32 vcc, v248, v153
	v_cmp_le_f32_e64 s[14:15], v248, v154
	v_and_b32_e32 v248, 0x7fffffff, v248
	s_and_b64 vcc, vcc, s[14:15]
	s_nop 1
	v_cndmask_b32_e32 v246, v249, v248, vcc
	v_cvt_pk_bf16_f32 v235, v245, v246
	v_add_f32_e32 v247, 0x43600000, v112
	v_cmp_ge_f32_e32 vcc, v247, v153
	v_cmp_le_f32_e64 s[14:15], v247, v154
	v_and_b32_e32 v247, 0x7fffffff, v247
	s_and_b64 vcc, vcc, s[14:15]
	s_nop 1
	v_cndmask_b32_e32 v245, v249, v247, vcc
	v_add_f32_e32 v248, 0x43610000, v112
; __global__ void __launch_bounds__(NTHREADS, 2) fwd_megakernel(Params p_arg) {
;     ...
;           float d0 = (float)(kt0 * 16 + fq * 4 - 128 - qi);
;           asm volatile("" : "+v"(d0));
;           const float lo2 = fmaxf(-128.f, klo - 128.f - (float)qi), hi2 = fminf(128.f, khi - 129.f - (float)qi);
;           float mx = sinkv;
; #pragma unroll
;           for (int i = 0; i < 18; ++i)
; #pragma unroll
;             for (int r = 0; r < 4; ++r) {
;               float t = d0 + (float)(i * 16 + r);
;               bool ok = (t >= lo2) && (t <= hi2);
;               float v = ok ? (S[i][r] - slope * fabsf(t)) : -1e30f;
;               S[i][r] = v; mx = fmaxf(mx, v);
	v_cmp_ge_f32_e32 vcc, v248, v153
	v_cmp_le_f32_e64 s[14:15], v248, v154
	v_and_b32_e32 v248, 0x7fffffff, v248
	s_and_b64 vcc, vcc, s[14:15]
	s_nop 1
	v_cndmask_b32_e32 v246, v249, v248, vcc
	v_cvt_pk_bf16_f32 v236, v245, v246
	v_add_f32_e32 v247, 0x43620000, v112
	v_cmp_ge_f32_e32 vcc, v247, v153
	v_cmp_le_f32_e64 s[14:15], v247, v154
	v_and_b32_e32 v247, 0x7fffffff, v247
	s_and_b64 vcc, vcc, s[14:15]
	s_nop 1
	v_cndmask_b32_e32 v245, v249, v247, vcc
	v_add_f32_e32 v248, 0x43630000, v112
	v_cmp_ge_f32_e32 vcc, v248, v153
	v_cmp_le_f32_e64 s[14:15], v248, v154
	v_and_b32_e32 v248, 0x7fffffff, v248
	s_and_b64 vcc, vcc, s[14:15]
	s_nop 1
	v_cndmask_b32_e32 v246, v249, v248, vcc
	v_cvt_pk_bf16_f32 v237, v245, v246
	v_add_f32_e32 v247, 0x43700000, v112
	v_cmp_ge_f32_e32 vcc, v247, v153
	v_cmp_le_f32_e64 s[14:15], v247, v154
	v_and_b32_e32 v247, 0x7fffffff, v247
	s_and_b64 vcc, vcc, s[14:15]
	s_nop 1
	v_cndmask_b32_e32 v245, v249, v247, vcc
	v_add_f32_e32 v248, 0x43710000, v112
	v_cmp_ge_f32_e32 vcc, v248, v153
	v_cmp_le_f32_e64 s[14:15], v248, v154
	v_and_b32_e32 v248, 0x7fffffff, v248
	s_and_b64 vcc, vcc, s[14:15]
	s_nop 1
	v_cndmask_b32_e32 v246, v249, v248, vcc
	v_cvt_pk_bf16_f32 v238, v245, v246
	v_add_f32_e32 v247, 0x43720000, v112
	v_cmp_ge_f32_e32 vcc, v247, v153
	v_cmp_le_f32_e64 s[14:15], v247, v154
	v_and_b32_e32 v247, 0x7fffffff, v247
	s_and_b64 vcc, vcc, s[14:15]
	s_nop 1
	v_cndmask_b32_e32 v245, v249, v247, vcc
	v_add_f32_e32 v248, 0x43730000, v112
	v_cmp_ge_f32_e32 vcc, v248, v153
	v_cmp_le_f32_e64 s[14:15], v248, v154
	v_and_b32_e32 v248, 0x7fffffff, v248
	s_and_b64 vcc, vcc, s[14:15]
	s_nop 1
	v_cndmask_b32_e32 v246, v249, v248, vcc
	v_cvt_pk_bf16_f32 v239, v245, v246
	v_add_f32_e32 v247, 0x43800000, v112
	v_cmp_ge_f32_e32 vcc, v247, v153
	v_cmp_le_f32_e64 s[14:15], v247, v154
	v_and_b32_e32 v247, 0x7fffffff, v247
	s_and_b64 vcc, vcc, s[14:15]
	s_nop 1
	v_cndmask_b32_e32 v245, v249, v247, vcc
	v_add_f32_e32 v248, 0x43808000, v112
	v_cmp_ge_f32_e32 vcc, v248, v153
	v_cmp_le_f32_e64 s[14:15], v248, v154
	v_and_b32_e32 v248, 0x7fffffff, v248
	s_and_b64 vcc, vcc, s[14:15]
	s_nop 1
	v_cndmask_b32_e32 v246, v249, v248, vcc
	v_cvt_pk_bf16_f32 v240, v245, v246
	v_add_f32_e32 v247, 0x43810000, v112
	v_cmp_ge_f32_e32 vcc, v247, v153
	v_cmp_le_f32_e64 s[14:15], v247, v154
	v_and_b32_e32 v247, 0x7fffffff, v247
	s_and_b64 vcc, vcc, s[14:15]
	s_nop 1
	v_cndmask_b32_e32 v245, v249, v247, vcc
	v_add_f32_e32 v248, 0x43818000, v112
	v_cmp_ge_f32_e32 vcc, v248, v153
	v_cmp_le_f32_e64 s[14:15], v248, v154
	v_and_b32_e32 v248, 0x7fffffff, v248
	s_and_b64 vcc, vcc, s[14:15]
	s_nop 1
	v_cndmask_b32_e32 v246, v249, v248, vcc
	v_cvt_pk_bf16_f32 v241, v245, v246
	v_add_f32_e32 v247, 0x43880000, v112
	v_cmp_ge_f32_e32 vcc, v247, v153
	v_cmp_le_f32_e64 s[14:15], v247, v154
	v_and_b32_e32 v247, 0x7fffffff, v247
	s_and_b64 vcc, vcc, s[14:15]
	s_nop 1
	v_cndmask_b32_e32 v245, v249, v247, vcc
	v_add_f32_e32 v248, 0x43888000, v112
	v_cmp_ge_f32_e32 vcc, v248, v153
	v_cmp_le_f32_e64 s[14:15], v248, v154
	v_and_b32_e32 v248, 0x7fffffff, v248
	s_and_b64 vcc, vcc, s[14:15]
	s_nop 1
	v_cndmask_b32_e32 v246, v249, v248, vcc
	v_cvt_pk_bf16_f32 v242, v245, v246
	v_add_f32_e32 v247, 0x43890000, v112
	v_cmp_ge_f32_e32 vcc, v247, v153
	v_cmp_le_f32_e64 s[14:15], v247, v154
	v_and_b32_e32 v247, 0x7fffffff, v247
	s_and_b64 vcc, vcc, s[14:15]
	s_nop 1
	v_cndmask_b32_e32 v245, v249, v247, vcc
	v_add_f32_e32 v248, 0x43898000, v112
	v_cmp_ge_f32_e32 vcc, v248, v153
	v_cmp_le_f32_e64 s[14:15], v248, v154
	v_and_b32_e32 v248, 0x7fffffff, v248
	s_and_b64 vcc, vcc, s[14:15]
	s_nop 1
	v_cndmask_b32_e32 v246, v249, v248, vcc
	v_cvt_pk_bf16_f32 v243, v245, v246
	s_barrier
